# D attention loop: V tiles re-pitched 144->192 bytes in LDS so the transposed V-fragment reads are bank-conflict-free (strategy 6)
# baseline (speedup 1.0000x reference)
; #define ALAS __attribute__((address_space(3)))
; template <bool SUB> __device__ __forceinline__ void attn_unit_r2(const AU& u, ALAS unsigned char* lds, float mb2) {
;     ...
;     int tid_o = threadIdx.x; asm volatile("" : "+v"(tid_o));
;     const int tid = tid_o, lane = tid & 63, wid = __builtin_amdgcn_readfirstlane(tid >> 6), r = lane & 31, h = lane >> 5;
;     const int hl = wid / u.wph, qs = u.q0 + 64 * (wid % u.wph);
;     bf16x8 qa[4], qb[4];
;     { const bf16_t* qp = u.Q + (size_t)hl * u.qhs + (size_t)(qs + r) * u.qrs + h * 8;
; #pragma unroll
;       for (int d0 = 0; d0 < 4; ++d0) { qa[d0] = *(const bf16x8*)(qp + d0 * 16); qb[d0] = *(const bf16x8*)(qp + (size_t)32 * u.qrs + d0 * 16); } }
;     const int NT = u.nsub >> 6;
;     const int kr0 = tid >> 3, kc0 = tid & 7;
;     const bf16_t* kg0 = u.K + (size_t)kr0 * u.krs + kc0 * 8; const bf16_t* vg = u.V + (size_t)kr0 * u.vrs + kc0 * 8;
;     const int kl0 = kr0 * KP + kc0 * 16, vl = V_OFF + kr0 * VP + kc0 * 16;
;     f32x16 oa0, oa1, ob0, ob1, negm;
; #pragma unroll
;     for (int i = 0; i < 16; ++i) { oa0[i] = 0.f; oa1[i] = 0.f; ob0[i] = 0.f; ob1[i] = 0.f; negm[i] = SUB ? -mb2 : 0.f; }
;     float la = 0.f, lb = 0.f;
;     u32x4 rk = *(const u32x4*)kg0, rv = *(const u32x4*)vg;
;     *(ALAS u32x4*)(lds + kl0) = rk; *(ALAS u32x4*)(lds + vl) = rv;
;     __syncthreads();
;     for (int t = 0; t < NT; ++t) {
;         const int cur = t & 1;
;         if (t + 1 < NT) { const size_t ro = (size_t)(t + 1) * 64; rk = *(const u32x4*)(kg0 + ro * u.krs); rv = *(const u32x4*)(vg + ro * u.vrs); }
;         {
;             const ALAS unsigned char* kb = lds + cur * KBUF + r * KP + h * 16;
;             const ALAS unsigned char* vb = lds + V_OFF + cur * VBUF + (4 * h + ((lane & 15) >> 2)) * VP + ((lane >> 4) & 1) * 32 + (lane & 3) * 8;
.LBB0_169:
	s_and_b64 vcc, exec, s[52:53]
	s_cbranch_vccz .LBB0_117
	s_and_saveexec_b64 s[20:21], s[38:39]
	s_xor_b64 s[52:53], exec, s[20:21]
	s_cbranch_execz .LBB0_178
	v_mov_b32_e32 v22, v171
	v_mov_b64_e32 v[16:17], s[22:23]
	v_readfirstlane_b32 s2, v22
	s_ashr_i32 s2, s2, 6
	s_lshr_b32 s7, s2, 31
	s_add_i32 s7, s2, s7
	s_ashr_i32 s54, s7, 1
	s_and_b32 s7, s7, 0x3fffffe
	v_ashrrev_i32_e32 v23, 3, v22
	s_movk_i32 s30, 0xc00
	v_lshlrev_b32_e32 v18, 4, v22
	v_mov_b64_e32 v[20:21], s[4:5]
	s_sub_i32 s2, s2, s7
	v_mad_i64_i32 v[16:17], s[20:21], v23, s30, v[16:17]
	v_and_b32_e32 v18, 0x70, v18
	v_mad_i64_i32 v[20:21], s[20:21], v23, s30, v[20:21]
	v_mov_b32_e32 v19, v169
	s_lshl_b32 s2, s2, 6
	v_lshl_add_u64 v[20:21], v[20:21], 0, v[18:19]
	v_lshl_add_u64 v[16:17], v[16:17], 0, v[18:19]
	v_and_b32_e32 v19, 31, v22
	s_ashr_i32 s55, s54, 31
	s_add_i32 s2, s2, s79
	global_load_dwordx4 v[128:131], v[20:21], off
	global_load_dwordx4 v[132:135], v[16:17], off
	s_lshl_b64 s[54:55], s[54:55], 7
	v_or_b32_e32 v16, s2, v19
	s_movk_i32 s7, 0x600
	s_add_u32 s54, s48, s54
	v_mul_lo_u32 v16, v16, s7
	v_bfe_u32 v24, v22, 5, 1
	s_addc_u32 s55, s49, s55
	v_ashrrev_i32_e32 v17, 31, v16
	v_lshlrev_b32_e32 v168, 4, v24
	v_lshl_add_u64 v[16:17], v[16:17], 1, s[54:55]
	v_lshl_add_u64 v[16:17], v[16:17], 0, v[168:169]
	s_mov_b32 s7, 0x18000
	v_add_co_u32_e32 v20, vcc, s7, v16
	v_bfe_u32 v25, v22, 2, 2
	s_nop 0
	v_addc_co_u32_e32 v21, vcc, 0, v17, vcc
	global_load_dwordx4 v[136:139], v[16:17], off
	global_load_dwordx4 v[140:143], v[16:17], off offset:32
	global_load_dwordx4 v[144:147], v[16:17], off offset:64
	global_load_dwordx4 v[148:151], v[16:17], off offset:96
	global_load_dwordx4 v[152:155], v[20:21], off
	global_load_dwordx4 v[156:159], v[20:21], off offset:32
	global_load_dwordx4 v[160:163], v[20:21], off offset:64
	global_load_dwordx4 v[164:167], v[20:21], off offset:96
	v_lshlrev_b32_e32 v16, 1, v22
	v_lshlrev_b32_e32 v17, 3, v22
	s_movk_i32 s7, 0x90
	v_mul_u32_u24_e32 v19, 0x90, v19
	v_lshl_or_b32 v21, v24, 2, v25
	v_and_b32_e32 v22, 32, v16
	v_and_b32_e32 v24, 24, v17
	v_mad_i64_i32 v[16:17], s[54:55], v23, s30, 0
	v_mul_lo_u32 v20, v23, s7
	v_add3_u32 v168, 0, v19, v168
	v_mad_u32_u24 v19, v21, s7, 0
	v_or_b32_e32 v16, v16, v18
	v_mov_b32_e32 v48, 0
	v_add3_u32 v220, v18, v20, 0
	v_add3_u32 v221, v19, v22, v24
	v_lshl_add_u64 v[18:19], s[4:5], 0, v[16:17]
	v_lshl_add_u64 v[16:17], s[22:23], 0, v[16:17]
	s_mov_b32 s21, 0
	v_mov_b32_e32 v49, v48
	v_mov_b32_e32 v50, v48
	v_mov_b32_e32 v51, v48
	v_mov_b32_e32 v52, v48
	v_mov_b32_e32 v53, v48
	v_mov_b32_e32 v54, v48
	v_mov_b32_e32 v55, v48
	v_mov_b32_e32 v56, v48
	v_mov_b32_e32 v57, v48
	v_mov_b32_e32 v58, v48
	v_lshl_add_u64 v[174:175], v[18:19], 0, s[12:13]
	v_lshl_add_u64 v[176:177], v[16:17], 0, s[12:13]
	s_lshr_b32 s7, s78, 6
	v_mov_b32_e32 v59, v48
	v_mov_b32_e32 v60, v48
	v_mov_b32_e32 v61, v48
	v_mov_b32_e32 v62, v48
	v_mov_b32_e32 v63, v48
	v_mov_b32_e32 v64, v48
	v_mov_b32_e32 v65, v48
	v_mov_b32_e32 v66, v48
	v_mov_b32_e32 v67, v48
	v_mov_b32_e32 v68, v48
	v_mov_b32_e32 v69, v48
	v_mov_b32_e32 v70, v48
	v_mov_b32_e32 v71, v48
	v_mov_b32_e32 v72, v48
	v_mov_b32_e32 v73, v48
	v_mov_b32_e32 v74, v48
	v_mov_b32_e32 v75, v48
	v_mov_b32_e32 v76, v48
	v_mov_b32_e32 v77, v48
	v_mov_b32_e32 v78, v48
	v_mov_b32_e32 v79, v48
	v_mov_b32_e32 v16, v48
	v_mov_b32_e32 v17, v48
	v_mov_b32_e32 v18, v48
	v_mov_b32_e32 v19, v48
	v_mov_b32_e32 v20, v48
	v_mov_b32_e32 v21, v48
	v_mov_b32_e32 v22, v48
	v_mov_b32_e32 v23, v48
	v_mov_b32_e32 v24, v48
	v_mov_b32_e32 v25, v48
	v_mov_b32_e32 v26, v48
	v_mov_b32_e32 v27, v48
	v_mov_b32_e32 v28, v48
	v_mov_b32_e32 v29, v48
	v_mov_b32_e32 v30, v48
	v_mov_b32_e32 v31, v48
	v_mov_b32_e32 v32, v48
	v_mov_b32_e32 v33, v48
	v_mov_b32_e32 v34, v48
	v_mov_b32_e32 v35, v48
	v_mov_b32_e32 v36, v48
	v_mov_b32_e32 v37, v48
	v_mov_b32_e32 v38, v48
	v_mov_b32_e32 v39, v48
	v_mov_b32_e32 v40, v48
	v_mov_b32_e32 v41, v48
	v_mov_b32_e32 v42, v48
	v_mov_b32_e32 v43, v48
	v_mov_b32_e32 v44, v48
	v_mov_b32_e32 v45, v48
	v_mov_b32_e32 v46, v48
	v_mov_b32_e32 v47, v48
	v_mov_b32_e32 v172, v48
	v_mov_b32_e32 v173, v48
	v_lshrrev_b32_e32 v198, 3, v171
	v_and_b32_e32 v199, 63, v171
	v_mul_u32_u24_e32 v198, 48, v198
	v_lshrrev_b32_e32 v80, 5, v199
	v_bfe_u32 v81, v199, 2, 2
	v_add_u32_e32 v198, v198, v220
	v_lshl_or_b32 v80, v80, 2, v81
	v_mul_u32_u24_e32 v80, 48, v80
	v_add_u32_e32 v199, v80, v221
	v_mov_b32_e32 v242, v48
	v_mov_b32_e32 v243, v48
	v_mov_b32_e32 v112, v48
	v_mov_b32_e32 v113, v48
	v_mov_b32_e32 v114, v48
	v_mov_b32_e32 v115, v48
	v_mov_b32_e32 v116, v48
	v_mov_b32_e32 v117, v48
	v_mov_b32_e32 v118, v48
	v_mov_b32_e32 v119, v48
	v_mov_b32_e32 v120, v48
	v_mov_b32_e32 v121, v48
	v_mov_b32_e32 v122, v48
	v_mov_b32_e32 v123, v48
	v_mov_b32_e32 v124, v48
	v_mov_b32_e32 v125, v48
	v_mov_b32_e32 v126, v48
	v_mov_b32_e32 v127, v48
	v_mov_b32_e32 v0, v48
	v_mov_b32_e32 v1, v48
	v_mov_b32_e32 v2, v48
	v_mov_b32_e32 v3, v48
	v_mov_b32_e32 v4, v48
	v_mov_b32_e32 v5, v48
	v_mov_b32_e32 v6, v48
	v_mov_b32_e32 v7, v48
	v_mov_b32_e32 v8, v48
	v_mov_b32_e32 v9, v48
	v_mov_b32_e32 v10, v48
	v_mov_b32_e32 v11, v48
	v_mov_b32_e32 v12, v48
	v_mov_b32_e32 v13, v48
	v_mov_b32_e32 v14, v48
	v_mov_b32_e32 v15, v48
	v_mov_b32_e32 v80, v48
	v_mov_b32_e32 v81, v48
	v_mov_b32_e32 v82, v48
	v_mov_b32_e32 v83, v48
	v_mov_b32_e32 v84, v48
	v_mov_b32_e32 v85, v48
	v_mov_b32_e32 v86, v48
	v_mov_b32_e32 v87, v48
	v_mov_b32_e32 v88, v48
	v_mov_b32_e32 v89, v48
	v_mov_b32_e32 v90, v48
	v_mov_b32_e32 v91, v48
	v_mov_b32_e32 v92, v48
	v_mov_b32_e32 v93, v48
	v_mov_b32_e32 v94, v48
	v_mov_b32_e32 v95, v48
	v_mov_b32_e32 v96, v48
	v_mov_b32_e32 v97, v48
	v_mov_b32_e32 v98, v48
	v_mov_b32_e32 v99, v48
	v_mov_b32_e32 v100, v48
	v_mov_b32_e32 v101, v48
	v_mov_b32_e32 v102, v48
	v_mov_b32_e32 v103, v48
	v_mov_b32_e32 v104, v48
	v_mov_b32_e32 v105, v48
	v_mov_b32_e32 v106, v48
	v_mov_b32_e32 v107, v48
	v_mov_b32_e32 v108, v48
	v_mov_b32_e32 v109, v48
	v_mov_b32_e32 v110, v48
	v_mov_b32_e32 v111, v48
	v_mov_b32_e32 v178, v48
	v_mov_b32_e32 v179, v48
	v_mov_b32_e32 v180, v48
	v_mov_b32_e32 v181, v48
	v_mov_b32_e32 v182, v48
	v_mov_b32_e32 v183, v48
	v_mov_b32_e32 v184, v48
	v_mov_b32_e32 v185, v48
	v_mov_b32_e32 v186, v48
	v_mov_b32_e32 v187, v48
	v_mov_b32_e32 v188, v48
	v_mov_b32_e32 v189, v48
	v_mov_b32_e32 v190, v48
	v_mov_b32_e32 v191, v48
	v_mov_b32_e32 v192, v48
	v_mov_b32_e32 v193, v48
	v_mov_b32_e32 v194, v48
	v_mov_b32_e32 v195, v48
	v_mov_b32_e32 v196, v48
	v_mov_b32_e32 v197, v48
	v_mov_b32_e32 v210, v48
	v_mov_b32_e32 v211, v48
	v_mov_b32_e32 v212, v48
	v_mov_b32_e32 v213, v48
	v_mov_b32_e32 v238, v48
	v_mov_b32_e32 v239, v48
	v_mov_b32_e32 v240, v48
	v_mov_b32_e32 v241, v48
	v_mov_b32_e32 v248, v48
	v_mov_b32_e32 v249, v48
	v_mov_b32_e32 v250, v48
	v_mov_b32_e32 v251, v48
	s_waitcnt vmcnt(9)
	ds_write_b128 v220, v[128:131]
	s_waitcnt vmcnt(0)
	ds_write_b128 v198, v[132:135] offset:18432
	s_waitcnt lgkmcnt(0)
	s_barrier
	s_branch .Lr2n_topA
; #define ALAS __attribute__((address_space(3)))
; __device__ __forceinline__ s16x4 vtr(const ALAS unsigned char* p) { return __builtin_bit_cast(s16x4, __builtin_amdgcn_ds_read_tr16_b64_v4i16((ALAS s16x4*)p)); }
; #define AMFMA(a, b, c) __builtin_amdgcn_mfma_f32_32x32x16_bf16((a), (b), (c), 0, 0, 0)
; template <bool SUB> __device__ __forceinline__ void attn_unit_r2(const AU& u, ALAS unsigned char* lds, float mb2) {
;     ...
;     for (int t = 0; t < NT; ++t) {
;         const int cur = t & 1;
;         if (t + 1 < NT) { const size_t ro = (size_t)(t + 1) * 64; rk = *(const u32x4*)(kg0 + ro * u.krs); rv = *(const u32x4*)(vg + ro * u.vrs); }
;         {
;             const ALAS unsigned char* kb = lds + cur * KBUF + r * KP + h * 16;
;             const ALAS unsigned char* vb = lds + V_OFF + cur * VBUF + (4 * h + ((lane & 15) >> 2)) * VP + ((lane >> 4) & 1) * 32 + (lane & 3) * 8;
;             f32x16 Sa0 = negm, Sa1 = negm, Sb0 = negm, Sb1 = negm;
; #pragma unroll
;             for (int d0 = 0; d0 < 4; ++d0) {
;                 const bf16x8 k0 = *(const ALAS bf16x8*)(kb + d0 * 32), k1 = *(const ALAS bf16x8*)(kb + 32 * KP + d0 * 32);
;                 Sa0 = AMFMA(k0, qa[d0], Sa0); Sa1 = AMFMA(k1, qa[d0], Sa1); Sb0 = AMFMA(k0, qb[d0], Sb0); Sb1 = AMFMA(k1, qb[d0], Sb1);
;             }
;             bf16x8 paa[4], pab[4];
;     ...
;             R2_SOFT(Sa0, Sa1, paa, la);
;             R2_SOFT(Sb0, Sb1, pab, lb);
;     ...
; #pragma unroll
;             for (int ks = 0; ks < 4; ++ks) {
;                 const s16x4 lo0 = vtr(vb + ks * 16 * VP), hi0 = vtr(vb + (ks * 16 + 8) * VP), lo1 = vtr(vb + ks * 16 * VP + 64), hi1 = vtr(vb + (ks * 16 + 8) * VP + 64);
;                 const bf16x8 vf0 = __builtin_shufflevector(lo0, hi0, 0, 1, 2, 3, 4, 5, 6, 7), vf1 = __builtin_shufflevector(lo1, hi1, 0, 1, 2, 3, 4, 5, 6, 7);
;                 oa0 = AMFMA(paa[ks], vf0, oa0); oa1 = AMFMA(paa[ks], vf1, oa1); ob0 = AMFMA(pab[ks], vf0, ob0); ob1 = AMFMA(pab[ks], vf1, ob1);
.Lr2n_topA:
	global_load_dwordx4 v[128:131], v[174:175], off
	global_load_dwordx4 v[132:135], v[176:177], off
	ds_read_b128 v[222:225], v168 offset:0
	ds_read_b128 v[226:229], v168 offset:32
	ds_read_b128 v[230:233], v168 offset:64
	ds_read_b128 v[234:237], v168 offset:96
	v_mfma_f32_32x32x16_bf16 v[48:63], v[178:181], v[238:241], v[48:63]
	v_add_f32_e32 v172, v96, v172
	v_add_f32_e32 v173, v80, v173
	v_add_f32_e32 v172, v97, v172
	v_add_f32_e32 v173, v81, v173
	v_mfma_f32_32x32x16_bf16 v[64:79], v[178:181], v[248:251], v[64:79]
	v_add_f32_e32 v172, v98, v172
	v_add_f32_e32 v173, v82, v173
	v_add_f32_e32 v172, v99, v172
	v_add_f32_e32 v173, v83, v173
	ds_read_b128 v[178:181], v168 offset:4608
	v_mfma_f32_32x32x16_bf16 v[16:31], v[182:185], v[238:241], v[16:31]
	v_add_f32_e32 v172, v100, v172
	v_add_f32_e32 v173, v84, v173
	v_add_f32_e32 v172, v101, v172
	v_add_f32_e32 v173, v85, v173
	v_mfma_f32_32x32x16_bf16 v[32:47], v[182:185], v[248:251], v[32:47]
	v_add_f32_e32 v172, v102, v172
	v_add_f32_e32 v173, v86, v173
	v_add_f32_e32 v172, v103, v172
	v_add_f32_e32 v173, v87, v173
	ds_read_b128 v[182:185], v168 offset:4640
	v_mfma_f32_32x32x16_bf16 v[48:63], v[186:189], v[194:197], v[48:63]
	v_add_f32_e32 v172, v104, v172
	v_add_f32_e32 v173, v88, v173
	v_add_f32_e32 v172, v105, v172
	v_add_f32_e32 v173, v89, v173
	v_mfma_f32_32x32x16_bf16 v[64:79], v[186:189], v[210:213], v[64:79]
	v_add_f32_e32 v172, v106, v172
	v_add_f32_e32 v173, v90, v173
	v_add_f32_e32 v172, v107, v172
	v_add_f32_e32 v173, v91, v173
	ds_read_b128 v[186:189], v168 offset:4672
	v_mfma_f32_32x32x16_bf16 v[16:31], v[190:193], v[194:197], v[16:31]
	v_add_f32_e32 v172, v108, v172
	v_add_f32_e32 v173, v92, v173
	v_add_f32_e32 v172, v109, v172
	v_add_f32_e32 v173, v93, v173
	v_mfma_f32_32x32x16_bf16 v[32:47], v[190:193], v[210:213], v[32:47]
	v_add_f32_e32 v172, v110, v172
	v_add_f32_e32 v173, v94, v173
	v_add_f32_e32 v172, v111, v172
	v_add_f32_e32 v173, v95, v173
	ds_read_b128 v[190:193], v168 offset:4704
	s_waitcnt lgkmcnt(4)
	v_mfma_f32_32x32x16_bf16 v[96:111], v[222:225], v[136:139], 0
	v_lshl_add_u64 v[174:175], v[174:175], 0, s[12:13]
	v_add_f32_e32 v242, v112, v242
	v_add_f32_e32 v243, v0, v243
	v_add_f32_e32 v242, v113, v242
	v_add_f32_e32 v243, v1, v243
	v_add_f32_e32 v242, v114, v242
	v_mfma_f32_32x32x16_bf16 v[96:111], v[226:229], v[140:143], v[96:111]
	v_lshl_add_u64 v[176:177], v[176:177], 0, s[12:13]
	v_add_f32_e32 v243, v2, v243
	v_add_f32_e32 v242, v115, v242
	v_add_f32_e32 v243, v3, v243
	v_add_f32_e32 v242, v116, v242
	v_add_f32_e32 v243, v4, v243
	v_mfma_f32_32x32x16_bf16 v[96:111], v[230:233], v[144:147], v[96:111]
	v_add_f32_e32 v242, v117, v242
	v_add_f32_e32 v243, v5, v243
	v_add_f32_e32 v242, v118, v242
	v_add_f32_e32 v243, v6, v243
	v_add_f32_e32 v242, v119, v242
	v_add_f32_e32 v243, v7, v243
	v_mfma_f32_32x32x16_bf16 v[96:111], v[234:237], v[148:151], v[96:111]
	v_add_f32_e32 v242, v120, v242
	v_add_f32_e32 v243, v8, v243
	v_add_f32_e32 v242, v121, v242
	v_add_f32_e32 v243, v9, v243
	v_add_f32_e32 v242, v122, v242
	v_add_f32_e32 v243, v10, v243
	v_add_f32_e32 v242, v123, v242
	v_add_f32_e32 v243, v11, v243
	v_mfma_f32_32x32x16_bf16 v[80:95], v[222:225], v[152:155], 0
	v_add_f32_e32 v242, v124, v242
	v_add_f32_e32 v243, v12, v243
	v_add_f32_e32 v242, v125, v242
	v_add_f32_e32 v243, v13, v243
	v_add_f32_e32 v242, v126, v242
	v_add_f32_e32 v243, v14, v243
	v_add_f32_e32 v242, v127, v242
	v_add_f32_e32 v243, v15, v243
	v_mfma_f32_32x32x16_bf16 v[80:95], v[226:229], v[156:159], v[80:95]
	v_exp_f32_e32 v96, v96
	v_exp_f32_e32 v97, v97
	v_exp_f32_e32 v98, v98
	v_exp_f32_e32 v99, v99
	v_mfma_f32_32x32x16_bf16 v[80:95], v[230:233], v[160:163], v[80:95]
	v_exp_f32_e32 v100, v100
	v_exp_f32_e32 v101, v101
	v_exp_f32_e32 v102, v102
	v_exp_f32_e32 v103, v103
	v_mfma_f32_32x32x16_bf16 v[80:95], v[234:237], v[164:167], v[80:95]
	v_exp_f32_e32 v104, v104
	v_exp_f32_e32 v105, v105
	v_exp_f32_e32 v106, v106
	v_exp_f32_e32 v107, v107
	s_waitcnt lgkmcnt(0)
; #define ALAS __attribute__((address_space(3)))
; __device__ __forceinline__ s16x4 vtr(const ALAS unsigned char* p) { return __builtin_bit_cast(s16x4, __builtin_amdgcn_ds_read_tr16_b64_v4i16((ALAS s16x4*)p)); }
; #define AMFMA(a, b, c) __builtin_amdgcn_mfma_f32_32x32x16_bf16((a), (b), (c), 0, 0, 0)
; template <bool SUB> __device__ __forceinline__ void attn_unit_r2(const AU& u, ALAS unsigned char* lds, float mb2) {
;     ...
;             for (int ks = 0; ks < 4; ++ks) {
;                 const s16x4 lo0 = vtr(vb + ks * 16 * VP), hi0 = vtr(vb + (ks * 16 + 8) * VP), lo1 = vtr(vb + ks * 16 * VP + 64), hi1 = vtr(vb + (ks * 16 + 8) * VP + 64);
;                 const bf16x8 vf0 = __builtin_shufflevector(lo0, hi0, 0, 1, 2, 3, 4, 5, 6, 7), vf1 = __builtin_shufflevector(lo1, hi1, 0, 1, 2, 3, 4, 5, 6, 7);
;                 oa0 = AMFMA(paa[ks], vf0, oa0); oa1 = AMFMA(paa[ks], vf1, oa1); ob0 = AMFMA(pab[ks], vf0, ob0); ob1 = AMFMA(pab[ks], vf1, ob1);
;             }
;         }
;         if (t + 1 < NT) { *(ALAS u32x4*)(lds + (cur ^ 1) * KBUF + kl0) = rk; *(ALAS u32x4*)(lds + (cur ^ 1) * VBUF + vl) = rv; }
;         __syncthreads();
	v_mfma_f32_32x32x16_bf16 v[112:127], v[178:181], v[136:139], 0
	v_exp_f32_e32 v108, v108
	v_exp_f32_e32 v109, v109
	v_exp_f32_e32 v110, v110
	v_exp_f32_e32 v111, v111
	v_mfma_f32_32x32x16_bf16 v[112:127], v[182:185], v[140:143], v[112:127]
	v_cvt_pk_bf16_f32 v222, v96, v97
	v_cvt_pk_bf16_f32 v223, v98, v99
	v_cvt_pk_bf16_f32 v224, v100, v101
	v_cvt_pk_bf16_f32 v225, v102, v103
	v_exp_f32_e32 v80, v80
	v_exp_f32_e32 v81, v81
	v_mfma_f32_32x32x16_bf16 v[112:127], v[186:189], v[144:147], v[112:127]
	v_exp_f32_e32 v82, v82
	v_exp_f32_e32 v83, v83
	v_exp_f32_e32 v84, v84
	v_exp_f32_e32 v85, v85
	v_mfma_f32_32x32x16_bf16 v[112:127], v[190:193], v[148:151], v[112:127]
	v_exp_f32_e32 v86, v86
	v_exp_f32_e32 v87, v87
	v_cvt_pk_bf16_f32 v230, v104, v105
	v_cvt_pk_bf16_f32 v231, v106, v107
	v_cvt_pk_bf16_f32 v232, v108, v109
	v_cvt_pk_bf16_f32 v233, v110, v111
	v_mfma_f32_32x32x16_bf16 v[0:15], v[178:181], v[152:155], 0
	v_exp_f32_e32 v88, v88
	v_exp_f32_e32 v89, v89
	v_exp_f32_e32 v90, v90
	v_exp_f32_e32 v91, v91
	ds_read_b64_tr_b16 v[238:239], v199 offset:18432
	ds_read_b64_tr_b16 v[240:241], v199 offset:19968
	ds_read_b64_tr_b16 v[248:249], v199 offset:18496
	ds_read_b64_tr_b16 v[250:251], v199 offset:20032
	v_mfma_f32_32x32x16_bf16 v[0:15], v[182:185], v[156:159], v[0:15]
	v_exp_f32_e32 v92, v92
	v_exp_f32_e32 v93, v93
	v_exp_f32_e32 v94, v94
	v_exp_f32_e32 v95, v95
	v_mfma_f32_32x32x16_bf16 v[0:15], v[186:189], v[160:163], v[0:15]
	v_cvt_pk_bf16_f32 v226, v80, v81
	v_cvt_pk_bf16_f32 v227, v82, v83
	v_cvt_pk_bf16_f32 v228, v84, v85
	v_cvt_pk_bf16_f32 v229, v86, v87
	v_exp_f32_e32 v112, v112
	v_exp_f32_e32 v113, v113
	v_mfma_f32_32x32x16_bf16 v[0:15], v[190:193], v[164:167], v[0:15]
	v_exp_f32_e32 v114, v114
	v_exp_f32_e32 v115, v115
	v_exp_f32_e32 v116, v116
	v_exp_f32_e32 v117, v117
	ds_read_b64_tr_b16 v[194:195], v199 offset:21504
	ds_read_b64_tr_b16 v[196:197], v199 offset:23040
	ds_read_b64_tr_b16 v[210:211], v199 offset:21568
	ds_read_b64_tr_b16 v[212:213], v199 offset:23104
	s_waitcnt lgkmcnt(4)
	v_mfma_f32_32x32x16_bf16 v[48:63], v[222:225], v[238:241], v[48:63]
	v_exp_f32_e32 v118, v118
	v_exp_f32_e32 v119, v119
	v_exp_f32_e32 v120, v120
	v_exp_f32_e32 v121, v121
	v_mfma_f32_32x32x16_bf16 v[64:79], v[222:225], v[248:251], v[64:79]
	v_cvt_pk_bf16_f32 v234, v88, v89
	v_cvt_pk_bf16_f32 v235, v90, v91
	v_cvt_pk_bf16_f32 v236, v92, v93
	v_cvt_pk_bf16_f32 v237, v94, v95
	v_exp_f32_e32 v122, v122
	v_exp_f32_e32 v123, v123
	v_mfma_f32_32x32x16_bf16 v[16:31], v[226:229], v[238:241], v[16:31]
	v_exp_f32_e32 v124, v124
	v_exp_f32_e32 v125, v125
	v_exp_f32_e32 v126, v126
	v_exp_f32_e32 v127, v127
	v_mfma_f32_32x32x16_bf16 v[32:47], v[226:229], v[248:251], v[32:47]
	ds_read_b64_tr_b16 v[238:239], v199 offset:24576
	ds_read_b64_tr_b16 v[240:241], v199 offset:26112
	ds_read_b64_tr_b16 v[248:249], v199 offset:24640
	ds_read_b64_tr_b16 v[250:251], v199 offset:26176
	v_exp_f32_e32 v0, v0
	v_exp_f32_e32 v1, v1
	v_exp_f32_e32 v2, v2
	v_exp_f32_e32 v3, v3
	s_waitcnt lgkmcnt(4)
	v_mfma_f32_32x32x16_bf16 v[48:63], v[230:233], v[194:197], v[48:63]
	v_exp_f32_e32 v4, v4
	v_exp_f32_e32 v5, v5
	v_exp_f32_e32 v6, v6
	v_exp_f32_e32 v7, v7
	v_mfma_f32_32x32x16_bf16 v[64:79], v[230:233], v[210:213], v[64:79]
	v_cvt_pk_bf16_f32 v178, v112, v113
	v_cvt_pk_bf16_f32 v179, v114, v115
	v_cvt_pk_bf16_f32 v180, v116, v117
	v_cvt_pk_bf16_f32 v181, v118, v119
	v_exp_f32_e32 v8, v8
	v_exp_f32_e32 v9, v9
	v_mfma_f32_32x32x16_bf16 v[16:31], v[234:237], v[194:197], v[16:31]
	v_exp_f32_e32 v10, v10
	v_exp_f32_e32 v11, v11
	v_exp_f32_e32 v12, v12
	v_exp_f32_e32 v13, v13
	v_mfma_f32_32x32x16_bf16 v[32:47], v[234:237], v[210:213], v[32:47]
	ds_read_b64_tr_b16 v[194:195], v199 offset:27648
	ds_read_b64_tr_b16 v[196:197], v199 offset:29184
	ds_read_b64_tr_b16 v[210:211], v199 offset:27712
	ds_read_b64_tr_b16 v[212:213], v199 offset:29248
	v_exp_f32_e32 v14, v14
	v_exp_f32_e32 v15, v15
	v_cvt_pk_bf16_f32 v182, v0, v1
	v_cvt_pk_bf16_f32 v183, v2, v3
	v_cvt_pk_bf16_f32 v184, v4, v5
	v_cvt_pk_bf16_f32 v185, v6, v7
	v_cvt_pk_bf16_f32 v186, v120, v121
	v_cvt_pk_bf16_f32 v187, v122, v123
	v_cvt_pk_bf16_f32 v188, v124, v125
	v_cvt_pk_bf16_f32 v189, v126, v127
	v_cvt_pk_bf16_f32 v190, v8, v9
	v_cvt_pk_bf16_f32 v191, v10, v11
	v_cvt_pk_bf16_f32 v192, v12, v13
	v_cvt_pk_bf16_f32 v193, v14, v15
	s_waitcnt vmcnt(0)
	ds_write_b128 v220, v[128:131] offset:9216
	ds_write_b128 v198, v[132:135] offset:30720
	s_waitcnt lgkmcnt(0)
	s_barrier

; #define ALAS __attribute__((address_space(3)))
; __device__ __forceinline__ s16x4 vtr(const ALAS unsigned char* p) { return __builtin_bit_cast(s16x4, __builtin_amdgcn_ds_read_tr16_b64_v4i16((ALAS s16x4*)p)); }
; #define AMFMA(a, b, c) __builtin_amdgcn_mfma_f32_32x32x16_bf16((a), (b), (c), 0, 0, 0)
; template <bool SUB> __device__ __forceinline__ void attn_unit_r2(const AU& u, ALAS unsigned char* lds, float mb2) {
;     ...
;     for (int t = 0; t < NT; ++t) {
;         const int cur = t & 1;
;         if (t + 1 < NT) { const size_t ro = (size_t)(t + 1) * 64; rk = *(const u32x4*)(kg0 + ro * u.krs); rv = *(const u32x4*)(vg + ro * u.vrs); }
;         {
;             const ALAS unsigned char* kb = lds + cur * KBUF + r * KP + h * 16;
;             const ALAS unsigned char* vb = lds + V_OFF + cur * VBUF + (4 * h + ((lane & 15) >> 2)) * VP + ((lane >> 4) & 1) * 32 + (lane & 3) * 8;
;             f32x16 Sa0 = negm, Sa1 = negm, Sb0 = negm, Sb1 = negm;
; #pragma unroll
;             for (int d0 = 0; d0 < 4; ++d0) {
;                 const bf16x8 k0 = *(const ALAS bf16x8*)(kb + d0 * 32), k1 = *(const ALAS bf16x8*)(kb + 32 * KP + d0 * 32);
;                 Sa0 = AMFMA(k0, qa[d0], Sa0); Sa1 = AMFMA(k1, qa[d0], Sa1); Sb0 = AMFMA(k0, qb[d0], Sb0); Sb1 = AMFMA(k1, qb[d0], Sb1);
;             }
;             bf16x8 paa[4], pab[4];
;     ...
;             R2_SOFT(Sa0, Sa1, paa, la);
;             R2_SOFT(Sb0, Sb1, pab, lb);
;     ...
; #pragma unroll
;             for (int ks = 0; ks < 4; ++ks) {
;                 const s16x4 lo0 = vtr(vb + ks * 16 * VP), hi0 = vtr(vb + (ks * 16 + 8) * VP), lo1 = vtr(vb + ks * 16 * VP + 64), hi1 = vtr(vb + (ks * 16 + 8) * VP + 64);
;                 const bf16x8 vf0 = __builtin_shufflevector(lo0, hi0, 0, 1, 2, 3, 4, 5, 6, 7), vf1 = __builtin_shufflevector(lo1, hi1, 0, 1, 2, 3, 4, 5, 6, 7);
;                 oa0 = AMFMA(paa[ks], vf0, oa0); oa1 = AMFMA(paa[ks], vf1, oa1); ob0 = AMFMA(pab[ks], vf0, ob0); ob1 = AMFMA(pab[ks], vf1, ob1);
.Lr2n_noloadB:
	ds_read_b128 v[222:225], v168 offset:9216
	ds_read_b128 v[226:229], v168 offset:9248
	ds_read_b128 v[230:233], v168 offset:9280
	ds_read_b128 v[234:237], v168 offset:9312
	v_mfma_f32_32x32x16_bf16 v[48:63], v[178:181], v[238:241], v[48:63]
	v_add_f32_e32 v172, v96, v172
	v_add_f32_e32 v173, v80, v173
	v_add_f32_e32 v172, v97, v172
	v_add_f32_e32 v173, v81, v173
	v_mfma_f32_32x32x16_bf16 v[64:79], v[178:181], v[248:251], v[64:79]
	v_add_f32_e32 v172, v98, v172
	v_add_f32_e32 v173, v82, v173
	v_add_f32_e32 v172, v99, v172
	v_add_f32_e32 v173, v83, v173
	ds_read_b128 v[178:181], v168 offset:13824
	v_mfma_f32_32x32x16_bf16 v[16:31], v[182:185], v[238:241], v[16:31]
	v_add_f32_e32 v172, v100, v172
	v_add_f32_e32 v173, v84, v173
	v_add_f32_e32 v172, v101, v172
	v_add_f32_e32 v173, v85, v173
	v_mfma_f32_32x32x16_bf16 v[32:47], v[182:185], v[248:251], v[32:47]
	v_add_f32_e32 v172, v102, v172
	v_add_f32_e32 v173, v86, v173
	v_add_f32_e32 v172, v103, v172
	v_add_f32_e32 v173, v87, v173
	ds_read_b128 v[182:185], v168 offset:13856
	v_mfma_f32_32x32x16_bf16 v[48:63], v[186:189], v[194:197], v[48:63]
	v_add_f32_e32 v172, v104, v172
	v_add_f32_e32 v173, v88, v173
	v_add_f32_e32 v172, v105, v172
	v_add_f32_e32 v173, v89, v173
	v_mfma_f32_32x32x16_bf16 v[64:79], v[186:189], v[210:213], v[64:79]
	v_add_f32_e32 v172, v106, v172
	v_add_f32_e32 v173, v90, v173
	v_add_f32_e32 v172, v107, v172
	v_add_f32_e32 v173, v91, v173
	ds_read_b128 v[186:189], v168 offset:13888
	v_mfma_f32_32x32x16_bf16 v[16:31], v[190:193], v[194:197], v[16:31]
	v_add_f32_e32 v172, v108, v172
	v_add_f32_e32 v173, v92, v173
	v_add_f32_e32 v172, v109, v172
	v_add_f32_e32 v173, v93, v173
	v_mfma_f32_32x32x16_bf16 v[32:47], v[190:193], v[210:213], v[32:47]
	v_add_f32_e32 v172, v110, v172
	v_add_f32_e32 v173, v94, v173
	v_add_f32_e32 v172, v111, v172
	v_add_f32_e32 v173, v95, v173
	ds_read_b128 v[190:193], v168 offset:13920
	s_waitcnt lgkmcnt(4)
	v_mfma_f32_32x32x16_bf16 v[96:111], v[222:225], v[136:139], 0
	v_lshl_add_u64 v[174:175], v[174:175], 0, s[12:13]
	v_add_f32_e32 v242, v112, v242
	v_add_f32_e32 v243, v0, v243
	v_add_f32_e32 v242, v113, v242
	v_add_f32_e32 v243, v1, v243
	v_add_f32_e32 v242, v114, v242
	v_mfma_f32_32x32x16_bf16 v[96:111], v[226:229], v[140:143], v[96:111]
	v_lshl_add_u64 v[176:177], v[176:177], 0, s[12:13]
	v_add_f32_e32 v243, v2, v243
	v_add_f32_e32 v242, v115, v242
	v_add_f32_e32 v243, v3, v243
	v_add_f32_e32 v242, v116, v242
	v_add_f32_e32 v243, v4, v243
	v_mfma_f32_32x32x16_bf16 v[96:111], v[230:233], v[144:147], v[96:111]
	v_add_f32_e32 v242, v117, v242
	v_add_f32_e32 v243, v5, v243
	v_add_f32_e32 v242, v118, v242
	v_add_f32_e32 v243, v6, v243
	v_add_f32_e32 v242, v119, v242
	v_add_f32_e32 v243, v7, v243
	v_mfma_f32_32x32x16_bf16 v[96:111], v[234:237], v[148:151], v[96:111]
	v_add_f32_e32 v242, v120, v242
	v_add_f32_e32 v243, v8, v243
	v_add_f32_e32 v242, v121, v242
	v_add_f32_e32 v243, v9, v243
	v_add_f32_e32 v242, v122, v242
	v_add_f32_e32 v243, v10, v243
	v_add_f32_e32 v242, v123, v242
	v_add_f32_e32 v243, v11, v243
	v_mfma_f32_32x32x16_bf16 v[80:95], v[222:225], v[152:155], 0
	v_add_f32_e32 v242, v124, v242
	v_add_f32_e32 v243, v12, v243
	v_add_f32_e32 v242, v125, v242
	v_add_f32_e32 v243, v13, v243
	v_add_f32_e32 v242, v126, v242
	v_add_f32_e32 v243, v14, v243
	v_add_f32_e32 v242, v127, v242
	v_add_f32_e32 v243, v15, v243
	v_mfma_f32_32x32x16_bf16 v[80:95], v[226:229], v[156:159], v[80:95]
	v_exp_f32_e32 v96, v96
	v_exp_f32_e32 v97, v97
	v_exp_f32_e32 v98, v98
	v_exp_f32_e32 v99, v99
	v_mfma_f32_32x32x16_bf16 v[80:95], v[230:233], v[160:163], v[80:95]
	v_exp_f32_e32 v100, v100
	v_exp_f32_e32 v101, v101
	v_exp_f32_e32 v102, v102
	v_exp_f32_e32 v103, v103
	v_mfma_f32_32x32x16_bf16 v[80:95], v[234:237], v[164:167], v[80:95]
	v_exp_f32_e32 v104, v104
	v_exp_f32_e32 v105, v105
	v_exp_f32_e32 v106, v106
	v_exp_f32_e32 v107, v107
	s_waitcnt lgkmcnt(0)
; #define ALAS __attribute__((address_space(3)))
; __device__ __forceinline__ s16x4 vtr(const ALAS unsigned char* p) { return __builtin_bit_cast(s16x4, __builtin_amdgcn_ds_read_tr16_b64_v4i16((ALAS s16x4*)p)); }
; #define AMFMA(a, b, c) __builtin_amdgcn_mfma_f32_32x32x16_bf16((a), (b), (c), 0, 0, 0)
; template <bool SUB> __device__ __forceinline__ void attn_unit_r2(const AU& u, ALAS unsigned char* lds, float mb2) {
;     ...
;             for (int ks = 0; ks < 4; ++ks) {
;                 const s16x4 lo0 = vtr(vb + ks * 16 * VP), hi0 = vtr(vb + (ks * 16 + 8) * VP), lo1 = vtr(vb + ks * 16 * VP + 64), hi1 = vtr(vb + (ks * 16 + 8) * VP + 64);
;                 const bf16x8 vf0 = __builtin_shufflevector(lo0, hi0, 0, 1, 2, 3, 4, 5, 6, 7), vf1 = __builtin_shufflevector(lo1, hi1, 0, 1, 2, 3, 4, 5, 6, 7);
;                 oa0 = AMFMA(paa[ks], vf0, oa0); oa1 = AMFMA(paa[ks], vf1, oa1); ob0 = AMFMA(pab[ks], vf0, ob0); ob1 = AMFMA(pab[ks], vf1, ob1);
;             }
;         }
;         if (t + 1 < NT) { *(ALAS u32x4*)(lds + (cur ^ 1) * KBUF + kl0) = rk; *(ALAS u32x4*)(lds + (cur ^ 1) * VBUF + vl) = rv; }
;         __syncthreads();
	v_mfma_f32_32x32x16_bf16 v[112:127], v[178:181], v[136:139], 0
	v_exp_f32_e32 v108, v108
	v_exp_f32_e32 v109, v109
	v_exp_f32_e32 v110, v110
	v_exp_f32_e32 v111, v111
	v_mfma_f32_32x32x16_bf16 v[112:127], v[182:185], v[140:143], v[112:127]
	v_cvt_pk_bf16_f32 v222, v96, v97
	v_cvt_pk_bf16_f32 v223, v98, v99
	v_cvt_pk_bf16_f32 v224, v100, v101
	v_cvt_pk_bf16_f32 v225, v102, v103
	v_exp_f32_e32 v80, v80
	v_exp_f32_e32 v81, v81
	v_mfma_f32_32x32x16_bf16 v[112:127], v[186:189], v[144:147], v[112:127]
	v_exp_f32_e32 v82, v82
	v_exp_f32_e32 v83, v83
	v_exp_f32_e32 v84, v84
	v_exp_f32_e32 v85, v85
	v_mfma_f32_32x32x16_bf16 v[112:127], v[190:193], v[148:151], v[112:127]
	v_exp_f32_e32 v86, v86
	v_exp_f32_e32 v87, v87
	v_cvt_pk_bf16_f32 v230, v104, v105
	v_cvt_pk_bf16_f32 v231, v106, v107
	v_cvt_pk_bf16_f32 v232, v108, v109
	v_cvt_pk_bf16_f32 v233, v110, v111
	v_mfma_f32_32x32x16_bf16 v[0:15], v[178:181], v[152:155], 0
	v_exp_f32_e32 v88, v88
	v_exp_f32_e32 v89, v89
	v_exp_f32_e32 v90, v90
	v_exp_f32_e32 v91, v91
	ds_read_b64_tr_b16 v[238:239], v199 offset:30720
	ds_read_b64_tr_b16 v[240:241], v199 offset:32256
	ds_read_b64_tr_b16 v[248:249], v199 offset:30784
	ds_read_b64_tr_b16 v[250:251], v199 offset:32320
	v_mfma_f32_32x32x16_bf16 v[0:15], v[182:185], v[156:159], v[0:15]
	v_exp_f32_e32 v92, v92
	v_exp_f32_e32 v93, v93
	v_exp_f32_e32 v94, v94
	v_exp_f32_e32 v95, v95
	v_mfma_f32_32x32x16_bf16 v[0:15], v[186:189], v[160:163], v[0:15]
	v_cvt_pk_bf16_f32 v226, v80, v81
	v_cvt_pk_bf16_f32 v227, v82, v83
	v_cvt_pk_bf16_f32 v228, v84, v85
	v_cvt_pk_bf16_f32 v229, v86, v87
	v_exp_f32_e32 v112, v112
	v_exp_f32_e32 v113, v113
	v_mfma_f32_32x32x16_bf16 v[0:15], v[190:193], v[164:167], v[0:15]
	v_exp_f32_e32 v114, v114
	v_exp_f32_e32 v115, v115
	v_exp_f32_e32 v116, v116
	v_exp_f32_e32 v117, v117
	ds_read_b64_tr_b16 v[194:195], v199 offset:33792
	ds_read_b64_tr_b16 v[196:197], v199 offset:35328
	ds_read_b64_tr_b16 v[210:211], v199 offset:33856
	ds_read_b64_tr_b16 v[212:213], v199 offset:35392
	s_waitcnt lgkmcnt(4)
	v_mfma_f32_32x32x16_bf16 v[48:63], v[222:225], v[238:241], v[48:63]
	v_exp_f32_e32 v118, v118
	v_exp_f32_e32 v119, v119
	v_exp_f32_e32 v120, v120
	v_exp_f32_e32 v121, v121
	v_mfma_f32_32x32x16_bf16 v[64:79], v[222:225], v[248:251], v[64:79]
	v_cvt_pk_bf16_f32 v234, v88, v89
	v_cvt_pk_bf16_f32 v235, v90, v91
	v_cvt_pk_bf16_f32 v236, v92, v93
	v_cvt_pk_bf16_f32 v237, v94, v95
	v_exp_f32_e32 v122, v122
	v_exp_f32_e32 v123, v123
	v_mfma_f32_32x32x16_bf16 v[16:31], v[226:229], v[238:241], v[16:31]
	v_exp_f32_e32 v124, v124
	v_exp_f32_e32 v125, v125
	v_exp_f32_e32 v126, v126
	v_exp_f32_e32 v127, v127
	v_mfma_f32_32x32x16_bf16 v[32:47], v[226:229], v[248:251], v[32:47]
	ds_read_b64_tr_b16 v[238:239], v199 offset:36864
	ds_read_b64_tr_b16 v[240:241], v199 offset:38400
	ds_read_b64_tr_b16 v[248:249], v199 offset:36928
	ds_read_b64_tr_b16 v[250:251], v199 offset:38464
	v_exp_f32_e32 v0, v0
	v_exp_f32_e32 v1, v1
	v_exp_f32_e32 v2, v2
	v_exp_f32_e32 v3, v3
	s_waitcnt lgkmcnt(4)
	v_mfma_f32_32x32x16_bf16 v[48:63], v[230:233], v[194:197], v[48:63]
	v_exp_f32_e32 v4, v4
	v_exp_f32_e32 v5, v5
	v_exp_f32_e32 v6, v6
	v_exp_f32_e32 v7, v7
	v_mfma_f32_32x32x16_bf16 v[64:79], v[230:233], v[210:213], v[64:79]
	v_cvt_pk_bf16_f32 v178, v112, v113
	v_cvt_pk_bf16_f32 v179, v114, v115
	v_cvt_pk_bf16_f32 v180, v116, v117
	v_cvt_pk_bf16_f32 v181, v118, v119
	v_exp_f32_e32 v8, v8
	v_exp_f32_e32 v9, v9
	v_mfma_f32_32x32x16_bf16 v[16:31], v[234:237], v[194:197], v[16:31]
	v_exp_f32_e32 v10, v10
	v_exp_f32_e32 v11, v11
	v_exp_f32_e32 v12, v12
	v_exp_f32_e32 v13, v13
	s_andn2_b64 vcc, exec, s[54:55]
	v_mfma_f32_32x32x16_bf16 v[32:47], v[234:237], v[210:213], v[32:47]
	ds_read_b64_tr_b16 v[194:195], v199 offset:39936
	ds_read_b64_tr_b16 v[196:197], v199 offset:41472
	ds_read_b64_tr_b16 v[210:211], v199 offset:40000
	ds_read_b64_tr_b16 v[212:213], v199 offset:41536
	v_exp_f32_e32 v14, v14
	v_exp_f32_e32 v15, v15
	v_cvt_pk_bf16_f32 v182, v0, v1
	v_cvt_pk_bf16_f32 v183, v2, v3
	v_cvt_pk_bf16_f32 v184, v4, v5
	v_cvt_pk_bf16_f32 v185, v6, v7
	v_cvt_pk_bf16_f32 v186, v120, v121
	v_cvt_pk_bf16_f32 v187, v122, v123
	v_cvt_pk_bf16_f32 v188, v124, v125
	v_cvt_pk_bf16_f32 v189, v126, v127
	v_cvt_pk_bf16_f32 v190, v8, v9
	v_cvt_pk_bf16_f32 v191, v10, v11
	v_cvt_pk_bf16_f32 v192, v12, v13
	v_cvt_pk_bf16_f32 v193, v14, v15
	s_cbranch_vccnz .Lr2n_nowriteB
	s_waitcnt vmcnt(0)
	ds_write_b128 v220, v[128:131] offset:0
	ds_write_b128 v198, v[132:135] offset:18432
